# v109 with the per-16-row fragment skip (edit_skip2) instead of the 64-row wave skip in E1/E2
# speedup vs baseline: 1.0055x; 1.0055x over previous
; template <bool ABF, bool BBF, class RowF, class ColF, class Epi>
; __device__ __forceinline__ void gemm_tile(char* smem, int K, RowF rowptr, ColF colptr, int ldb, Epi epi) {
;     ...
;   constexpr int NA = ABF ? 4 : 8;
;   const int ar0 = ABF ? (tid >> 3) : (tid >> 4);
;   const int ac = ABF ? (tid & 7) * 8 : (tid & 15) * 4;
;   constexpr int ARS = ABF ? 32 : 16;
;   const char* ap[NA];
; #pragma unroll
;   for (int i = 0; i < NA; i++) ap[i] = (const char*)rowptr(ar0 + ARS * i) + ac * (ABF ? 2 : 4);
;   const int bc = tid & 127, kh = tid >> 7;
;   const float* bp = BBF ? nullptr : ((const float*)colptr(bc) + (size_t)(kh * 32) * ldb);
;   const int br0 = tid >> 3, bcc = (tid & 7) * 8;
;   const char* bq[4];
;   if (BBF) {
; #pragma unroll
;     for (int i = 0; i < 4; i++) bq[i] = (const char*)colptr(br0 + 32 * i) + bcc * 2;
;   }
; __device__ void phaseE1(const Params& p, char* smem) {
;     ...
;     const int rbg = q, jt = j;
;     int e = 0;
;     while (s_rb[e + 1] <= rbg) e++;
;     const int rb = rbg - s_rb[e];
;     const int cnt = p.cnt[e];
;     const int rows = min(128, cnt - rb * 128);
;     const int* lt = p.list_tok + e * CAP + rb * 128;
;     const int slot0 = s_off[e] + rb * 128;
;     const int j0 = jt * 64;
;     const u16* wg = p.WgT + (size_t)e * DEXP * DM;
;     const u16* wu = p.WuT + (size_t)e * DEXP * DM;
;     auto rowf = [&](int r) { int rr = r < rows ? r : 0; return (const void*)(p.X1B + (size_t)lt[rr] * DM); };
;     auto colf = [&](int c) { return (const void*)(((c & 32) ? wu : wg) + (size_t)(j0 + (c >> 6) * 32 + (c & 31)) * DM); };
.LBB0_1273:
	s_or_b64 exec, exec, s[16:17]
	s_cmp_lg_u32 s33, -1
	s_cselect_b32 s2, s33, 0
	s_cselect_b32 s16, s1, 0
	v_mov_b32_e32 v0, s2
	v_mov_b32_e32 v1, s16
	s_waitcnt lgkmcnt(0)
	s_barrier
	flat_load_dword v0, v[0:1] sc0 sc1
	s_waitcnt vmcnt(0)
	s_mov_b64 s[18:19], -1
	s_waitcnt lgkmcnt(0)
	v_cmp_lt_i32_e32 vcc, v0, v153
	s_and_saveexec_b64 s[16:17], vcc
	s_cbranch_execz .LBB0_1268
	v_readfirstlane_b32 s32, v0
	v_lshrrev_b32_e32 v90, 4, v128
	v_xor_b32_e32 v90, v90, v128
	v_and_b32_e32 v90, 7, v90
	v_lshlrev_b32_e32 v92, 4, v90
	v_mov_b32_e32 v93, 0
	v_sub_u32_e32 v94, v92, v124
	v_lshrrev_b32_e32 v90, 6, v128
	v_ashrrev_i32_e32 v95, 31, v94
	v_readfirstlane_b32 s100, v90
	s_lshl_b32 s100, s100, 10
	s_mov_b64 s[18:19], 0
	v_mbcnt_lo_u32_b32 v1, -1, 0
	v_mbcnt_hi_u32_b32 v1, -1, v1
	v_lshl_add_u32 v1, v1, 2, s25
	ds_read_b32 v1, v1
	s_waitcnt lgkmcnt(0)
	v_cmp_le_i32_e32 vcc, v1, v0
	s_bcnt1_i32_b64 s2, vcc
	v_mov_b32_e32 v96, s2
	s_or_b64 exec, exec, s[18:19]
	v_lshl_add_u32 v6, v96, 2, 0
	v_add_u32_e32 v6, 0x10000, v6
	ds_read2_b32 v[6:7], v6 offset1:1
	v_lshl_add_u32 v10, v96, 2, 0
	v_add_u32_e32 v1, 0x10120, v10
	ds_read_b32 v1, v1
	v_lshlrev_b32_e32 v2, 15, v96
	v_mov_b32_e32 v3, v97
	v_lshl_add_u64 v[2:3], v[2:3], 2, s[68:69]
	v_lshlrev_b64 v[4:5], 20, v[96:97]
	s_waitcnt lgkmcnt(0)
	v_sub_u32_e32 v6, v7, v6
	v_sub_u32_e32 v0, v0, v1
	v_lshlrev_b32_e32 v122, 7, v0
	v_ashrrev_i32_e32 v123, 31, v122
	v_lshl_add_u64 v[0:1], v[122:123], 2, v[2:3]
	v_mov_b32_e32 v56, 0
	s_mov_b32 s2, 0
	s_mov_b32 s27, 0
	v_mov_b32_e32 v57, v56
	v_mov_b32_e32 v58, v56
	v_mov_b32_e32 v59, v56
	v_mov_b32_e32 v48, v56
	v_mov_b32_e32 v49, v56
	v_mov_b32_e32 v50, v56
	v_mov_b32_e32 v51, v56
	v_mov_b32_e32 v60, v56
	v_mov_b32_e32 v61, v56
	v_mov_b32_e32 v62, v56
	v_mov_b32_e32 v63, v56
	v_mov_b32_e32 v52, v56
	v_mov_b32_e32 v53, v56
	v_mov_b32_e32 v54, v56
	v_mov_b32_e32 v55, v56
	v_mov_b32_e32 v40, v56
	v_mov_b32_e32 v41, v56
	v_mov_b32_e32 v42, v56
	v_mov_b32_e32 v43, v56
	v_mov_b32_e32 v32, v56
	v_mov_b32_e32 v33, v56
	v_mov_b32_e32 v34, v56
	v_mov_b32_e32 v35, v56
	v_mov_b32_e32 v44, v56
	v_mov_b32_e32 v45, v56
	v_mov_b32_e32 v46, v56
	v_mov_b32_e32 v47, v56
	v_mov_b32_e32 v36, v56
	v_mov_b32_e32 v37, v56
	v_mov_b32_e32 v38, v56
	v_mov_b32_e32 v39, v56
	v_mov_b32_e32 v24, v56
	v_mov_b32_e32 v25, v56
	v_mov_b32_e32 v26, v56
	v_mov_b32_e32 v27, v56
	v_mov_b32_e32 v16, v56
	v_mov_b32_e32 v17, v56
	v_mov_b32_e32 v18, v56
	v_mov_b32_e32 v19, v56
	v_mov_b32_e32 v28, v56
	v_mov_b32_e32 v29, v56
	v_mov_b32_e32 v30, v56
	v_mov_b32_e32 v31, v56
	v_mov_b32_e32 v20, v56
	v_mov_b32_e32 v21, v56
	v_mov_b32_e32 v22, v56
	v_mov_b32_e32 v23, v56
	s_waitcnt vmcnt(0)
	v_sub_u32_e32 v2, v6, v122
	v_min_i32_e32 v123, 0x80, v2
	v_cmp_lt_i32_e32 vcc, v160, v123
	v_readfirstlane_b32 s98, v123
	s_lshr_b32 s99, s100, 11
	s_lshl_b32 s99, s99, 6
	s_sub_i32 s99, s98, s99
	s_max_i32 s99, s99, 0
	s_min_i32 s99, s99, 64
	s_add_i32 s99, s99, 15
	s_lshr_b32 s99, s99, 4
	s_nop 1
	v_cndmask_b32_e32 v2, 0, v160, vcc
	v_cmp_lt_i32_e32 vcc, v150, v123
	v_lshlrev_b32_e32 v96, 2, v2
	v_lshl_add_u64 v[2:3], v[0:1], 0, v[96:97]
	v_cndmask_b32_e32 v6, 0, v150, vcc
	v_cmp_lt_i32_e32 vcc, v151, v123
	v_lshlrev_b32_e32 v96, 2, v6
	v_lshl_add_u64 v[6:7], v[0:1], 0, v[96:97]
	v_cndmask_b32_e32 v8, 0, v151, vcc
	v_cmp_lt_i32_e32 vcc, v152, v123
	v_lshlrev_b32_e32 v96, 2, v8
	v_lshl_add_u64 v[8:9], v[0:1], 0, v[96:97]
	v_cndmask_b32_e32 v11, 0, v152, vcc
	v_lshlrev_b32_e32 v96, 2, v11
	global_load_dword v2, v[2:3], off
	v_lshl_add_u64 v[0:1], v[0:1], 0, v[96:97]
	global_load_dword v6, v[6:7], off
	v_add_u32_e32 v96, 0x10000, v10
	global_load_dword v8, v[8:9], off
	v_lshl_add_u64 v[10:11], s[74:75], 0, v[4:5]
	global_load_dword v0, v[0:1], off
	v_lshl_add_u64 v[4:5], s[76:77], 0, v[4:5]
	v_cndmask_b32_e64 v133, v5, v11, s[6:7]
	v_cndmask_b32_e64 v132, v4, v10, s[6:7]
	v_cndmask_b32_e64 v135, v11, v5, s[6:7]
	v_cndmask_b32_e64 v134, v10, v4, s[6:7]
	v_cndmask_b32_e64 v137, v5, v11, s[8:9]
	v_cndmask_b32_e64 v136, v4, v10, s[8:9]
	v_lshl_add_u64 v[4:5], v[132:133], 0, v[112:113]
	v_lshl_add_u64 v[10:11], v[134:135], 0, v[114:115]
	v_lshl_add_u64 v[12:13], v[132:133], 0, v[116:117]
	v_lshl_add_u64 v[14:15], v[136:137], 0, v[118:119]
	v_lshl_add_u64 v[4:5], v[4:5], 0, v[92:93]
	v_lshl_add_u64 v[10:11], v[10:11], 0, v[92:93]
	v_lshl_add_u64 v[12:13], v[12:13], 0, v[92:93]
	v_lshl_add_u64 v[14:15], v[14:15], 0, v[92:93]
	s_add_u32 m0, s100, 0x4000
	s_nop 0
	global_load_lds_dwordx4 v[4:5], off
	s_add_u32 m0, s100, 0x5000
	s_nop 0
	global_load_lds_dwordx4 v[10:11], off
	s_add_u32 m0, s100, 0x6000
	s_nop 0
	global_load_lds_dwordx4 v[12:13], off
	s_add_u32 m0, s100, 0x7000
	s_nop 0
	global_load_lds_dwordx4 v[14:15], off
	v_lshl_add_u64 v[138:139], v[132:133], 0, s[4:5]
	v_lshl_add_u64 v[134:135], v[134:135], 0, v[106:107]
	v_lshl_add_u64 v[176:177], v[136:137], 0, v[110:111]
	v_mov_b32_e32 v10, v56
	v_mov_b32_e32 v11, v56
	v_mov_b32_e32 v12, v56
	v_mov_b32_e32 v13, v56
	v_mov_b32_e32 v14, v56
	v_mov_b32_e32 v15, v56
	v_lshl_add_u64 v[132:133], v[138:139], 0, v[104:105]
	v_lshl_add_u64 v[134:135], v[134:135], 0, s[4:5]
	v_lshl_add_u64 v[136:137], v[138:139], 0, v[108:109]
	v_lshl_add_u64 v[138:139], v[176:177], 0, s[4:5]
	s_waitcnt vmcnt(7)
	v_ashrrev_i32_e32 v3, 31, v2
	v_lshlrev_b64 v[140:141], 11, v[2:3]
	s_waitcnt vmcnt(6)
	v_ashrrev_i32_e32 v7, 31, v6
	v_lshl_add_u64 v[2:3], v[100:101], 0, v[140:141]
	s_waitcnt vmcnt(5)
	v_ashrrev_i32_e32 v9, 31, v8
	v_lshlrev_b64 v[144:145], 11, v[8:9]
	s_waitcnt vmcnt(4)
	v_ashrrev_i32_e32 v1, 31, v0
	v_lshlrev_b64 v[142:143], 11, v[6:7]
	v_lshl_add_u64 v[6:7], v[100:101], 0, v[144:145]
	v_lshlrev_b64 v[146:147], 11, v[0:1]
	v_lshl_add_u64 v[4:5], v[100:101], 0, v[142:143]
	s_add_u32 m0, s100, 0x0
	v_lshl_add_u64 v[90:91], v[2:3], 0, v[94:95]
	global_load_lds_dwordx4 v[90:91], off
	s_add_u32 m0, s100, 0x1000
	v_lshl_add_u64 v[90:91], v[4:5], 0, v[94:95]
	global_load_lds_dwordx4 v[90:91], off
	v_lshl_add_u64 v[0:1], v[100:101], 0, v[146:147]
	s_add_u32 m0, s100, 0x2000
	v_lshl_add_u64 v[90:91], v[6:7], 0, v[94:95]
	global_load_lds_dwordx4 v[90:91], off
	s_add_u32 m0, s100, 0x3000
	v_lshl_add_u64 v[90:91], v[0:1], 0, v[94:95]
	global_load_lds_dwordx4 v[90:91], off
	ds_read_b32 v96, v96
	v_mov_b32_e32 v8, v56
	v_mov_b32_e32 v9, v56
	v_mov_b32_e32 v0, v56
	v_mov_b32_e32 v1, v56
	v_mov_b32_e32 v2, v56
	v_mov_b32_e32 v3, v56
	v_mov_b32_e32 v4, v56
	v_mov_b32_e32 v5, v56
	v_mov_b32_e32 v6, v56
	v_lshl_add_u64 v[140:141], s[10:11], 0, v[140:141]
	v_lshl_add_u64 v[142:143], s[10:11], 0, v[142:143]
	v_lshl_add_u64 v[144:145], s[10:11], 0, v[144:145]
	v_lshl_add_u64 v[146:147], s[10:11], 0, v[146:147]
	v_mov_b32_e32 v7, v56
	s_waitcnt vmcnt(0)
	s_waitcnt lgkmcnt(0)
	s_barrier
	s_branch .LBB0_1278

; template <bool ABF, bool BBF, class RowF, class ColF, class Epi>
; __device__ __forceinline__ void gemm_tile(char* smem, int K, RowF rowptr, ColF colptr, int ldb, Epi epi) {
;     ...
;     {
;       bf16x8 af[2][4], bfr[2][4];
; #pragma unroll
;       for (int ks = 0; ks < 2; ks++) {
; #pragma unroll
;         for (int mi = 0; mi < 4; mi++) af[ks][mi] = *(const bf16x8*)&As[(wm * 64 + mi * 16 + l15) * LDT + (((ks * 4 + kg) ^ swz) << 3)];
; #pragma unroll
;         for (int ni = 0; ni < 4; ni++) bfr[ks][ni] = *(const bf16x8*)&Bs[(wn * 64 + ni * 16 + l15) * LDT + (((ks * 4 + kg) ^ swz) << 3)];
;       }
;       __builtin_amdgcn_sched_barrier(0);
; #pragma unroll
;       for (int ks = 0; ks < 2; ks++)
; #pragma unroll
;         for (int mi = 0; mi < 4; mi++)
; #pragma unroll
;           for (int ni = 0; ni < 4; ni++)
;             acc[mi][ni] = __builtin_amdgcn_mfma_f32_16x16x32_bf16(bfr[ks][ni], af[ks][mi], acc[mi][ni], 0, 0, 0);
;       __builtin_amdgcn_sched_barrier(0);
;     }
.LBB0_1280:
	s_cmp_lg_u32 s99, 4
	s_cbranch_scc1 .Le1_var
	s_lshl_b32 s28, s27, 15
	s_add_i32 s28, s28, 0
	v_lshlrev_b32_e32 v176, 1, v163
	v_add_u32_e32 v192, s28, v176
	v_lshlrev_b32_e32 v208, 1, v164
	v_lshl_add_u32 v224, v165, 1, s28
	v_add_u32_e32 v177, v192, v208
	v_add3_u32 v188, s28, v208, v176
	v_add_u32_e32 v204, v192, v175
	v_add_u32_e32 v220, v224, v208
	v_add_u32_e32 v236, v224, v175
	ds_read_b128 v[176:179], v177
	ds_read_b128 v[180:183], v188 offset:2048
	ds_read_b128 v[184:187], v188 offset:4096
	ds_read_b128 v[188:191], v188 offset:6144
	ds_read_b128 v[192:195], v204 offset:16384
	ds_read_b128 v[196:199], v204 offset:18432
	ds_read_b128 v[200:203], v204 offset:20480
	ds_read_b128 v[204:207], v204 offset:22528
	ds_read_b128 v[208:211], v220
	ds_read_b128 v[212:215], v220 offset:2048
	ds_read_b128 v[216:219], v220 offset:4096
	ds_read_b128 v[220:223], v220 offset:6144
	ds_read_b128 v[224:227], v236 offset:16384
	ds_read_b128 v[228:231], v236 offset:18432
	ds_read_b128 v[232:235], v236 offset:20480
	ds_read_b128 v[236:239], v236 offset:22528
	s_waitcnt lgkmcnt(11)
	v_mfma_f32_16x16x32_bf16 v[56:59], v[192:195], v[176:179], v[56:59]
	s_waitcnt lgkmcnt(10)
	v_mfma_f32_16x16x32_bf16 v[48:51], v[196:199], v[176:179], v[48:51]
	s_waitcnt lgkmcnt(9)
	v_mfma_f32_16x16x32_bf16 v[60:63], v[200:203], v[176:179], v[60:63]
	s_waitcnt lgkmcnt(8)
	v_mfma_f32_16x16x32_bf16 v[52:55], v[204:207], v[176:179], v[52:55]
	v_mfma_f32_16x16x32_bf16 v[40:43], v[192:195], v[180:183], v[40:43]
	v_mfma_f32_16x16x32_bf16 v[32:35], v[196:199], v[180:183], v[32:35]
	v_mfma_f32_16x16x32_bf16 v[44:47], v[200:203], v[180:183], v[44:47]
	v_mfma_f32_16x16x32_bf16 v[36:39], v[204:207], v[180:183], v[36:39]
	v_mfma_f32_16x16x32_bf16 v[24:27], v[192:195], v[184:187], v[24:27]
	v_mfma_f32_16x16x32_bf16 v[16:19], v[196:199], v[184:187], v[16:19]
	v_mfma_f32_16x16x32_bf16 v[28:31], v[200:203], v[184:187], v[28:31]
	v_mfma_f32_16x16x32_bf16 v[20:23], v[204:207], v[184:187], v[20:23]
	v_mfma_f32_16x16x32_bf16 v[8:11], v[192:195], v[188:191], v[8:11]
	v_mfma_f32_16x16x32_bf16 v[0:3], v[196:199], v[188:191], v[0:3]
	v_mfma_f32_16x16x32_bf16 v[12:15], v[200:203], v[188:191], v[12:15]
	v_mfma_f32_16x16x32_bf16 v[4:7], v[204:207], v[188:191], v[4:7]
	s_waitcnt lgkmcnt(3)
	v_mfma_f32_16x16x32_bf16 v[56:59], v[224:227], v[208:211], v[56:59]
	s_waitcnt lgkmcnt(2)
	v_mfma_f32_16x16x32_bf16 v[48:51], v[228:231], v[208:211], v[48:51]
	s_waitcnt lgkmcnt(1)
	v_mfma_f32_16x16x32_bf16 v[60:63], v[232:235], v[208:211], v[60:63]
	s_waitcnt lgkmcnt(0)
	v_mfma_f32_16x16x32_bf16 v[52:55], v[236:239], v[208:211], v[52:55]
	v_mfma_f32_16x16x32_bf16 v[40:43], v[224:227], v[212:215], v[40:43]
	v_mfma_f32_16x16x32_bf16 v[32:35], v[228:231], v[212:215], v[32:35]
	v_mfma_f32_16x16x32_bf16 v[44:47], v[232:235], v[212:215], v[44:47]
	v_mfma_f32_16x16x32_bf16 v[36:39], v[236:239], v[212:215], v[36:39]
	v_mfma_f32_16x16x32_bf16 v[24:27], v[224:227], v[216:219], v[24:27]
	v_mfma_f32_16x16x32_bf16 v[16:19], v[228:231], v[216:219], v[16:19]
	v_mfma_f32_16x16x32_bf16 v[28:31], v[232:235], v[216:219], v[28:31]
	v_mfma_f32_16x16x32_bf16 v[20:23], v[236:239], v[216:219], v[20:23]
	v_mfma_f32_16x16x32_bf16 v[8:11], v[224:227], v[220:223], v[8:11]
	v_mfma_f32_16x16x32_bf16 v[0:3], v[228:231], v[220:223], v[0:3]
	v_mfma_f32_16x16x32_bf16 v[12:15], v[232:235], v[220:223], v[12:15]
	v_mfma_f32_16x16x32_bf16 v[4:7], v[236:239], v[220:223], v[4:7]

; template <bool ABF, bool BBF, class RowF, class ColF, class Epi>
; __device__ __forceinline__ void gemm_tile(char* smem, int K, RowF rowptr, ColF colptr, int ldb, Epi epi) {
;     ...
;     {
;       bf16x8 af[2][4], bfr[2][4];
; #pragma unroll
;       for (int ks = 0; ks < 2; ks++) {
; #pragma unroll
;         for (int mi = 0; mi < 4; mi++) af[ks][mi] = *(const bf16x8*)&As[(wm * 64 + mi * 16 + l15) * LDT + (((ks * 4 + kg) ^ swz) << 3)];
; #pragma unroll
;         for (int ni = 0; ni < 4; ni++) bfr[ks][ni] = *(const bf16x8*)&Bs[(wn * 64 + ni * 16 + l15) * LDT + (((ks * 4 + kg) ^ swz) << 3)];
;       }
;       __builtin_amdgcn_sched_barrier(0);
; #pragma unroll
;       for (int ks = 0; ks < 2; ks++)
; #pragma unroll
;         for (int mi = 0; mi < 4; mi++)
; #pragma unroll
;           for (int ni = 0; ni < 4; ni++)
;             acc[mi][ni] = __builtin_amdgcn_mfma_f32_16x16x32_bf16(bfr[ks][ni], af[ks][mi], acc[mi][ni], 0, 0, 0);
;       __builtin_amdgcn_sched_barrier(0);
;     }
.Le1_var:
	s_cmp_eq_u32 s99, 0
	s_cbranch_scc1 .Le1_skipc
	s_cmp_eq_u32 s99, 1
	s_cbranch_scc1 .Le1_v1
	s_cmp_eq_u32 s99, 2
	s_cbranch_scc1 .Le1_v2
	s_lshl_b32 s28, s27, 15
	s_add_i32 s28, s28, 0
	v_lshlrev_b32_e32 v176, 1, v163
	v_add_u32_e32 v192, s28, v176
	v_lshlrev_b32_e32 v208, 1, v164
	v_lshl_add_u32 v224, v165, 1, s28
	v_add_u32_e32 v177, v192, v208
	v_add3_u32 v188, s28, v208, v176
	v_add_u32_e32 v204, v192, v175
	v_add_u32_e32 v220, v224, v208
	v_add_u32_e32 v236, v224, v175
	ds_read_b128 v[176:179], v177
	ds_read_b128 v[180:183], v188 offset:2048
	ds_read_b128 v[184:187], v188 offset:4096
	ds_read_b128 v[192:195], v204 offset:16384
	ds_read_b128 v[196:199], v204 offset:18432
	ds_read_b128 v[200:203], v204 offset:20480
	ds_read_b128 v[204:207], v204 offset:22528
	ds_read_b128 v[208:211], v220
	ds_read_b128 v[212:215], v220 offset:2048
	ds_read_b128 v[216:219], v220 offset:4096
	ds_read_b128 v[224:227], v236 offset:16384
	ds_read_b128 v[228:231], v236 offset:18432
	ds_read_b128 v[232:235], v236 offset:20480
	ds_read_b128 v[236:239], v236 offset:22528
	s_waitcnt lgkmcnt(0)
	v_mfma_f32_16x16x32_bf16 v[56:59], v[192:195], v[176:179], v[56:59]
	v_mfma_f32_16x16x32_bf16 v[48:51], v[196:199], v[176:179], v[48:51]
	v_mfma_f32_16x16x32_bf16 v[60:63], v[200:203], v[176:179], v[60:63]
	v_mfma_f32_16x16x32_bf16 v[52:55], v[204:207], v[176:179], v[52:55]
	v_mfma_f32_16x16x32_bf16 v[40:43], v[192:195], v[180:183], v[40:43]
	v_mfma_f32_16x16x32_bf16 v[32:35], v[196:199], v[180:183], v[32:35]
	v_mfma_f32_16x16x32_bf16 v[44:47], v[200:203], v[180:183], v[44:47]
	v_mfma_f32_16x16x32_bf16 v[36:39], v[204:207], v[180:183], v[36:39]
	v_mfma_f32_16x16x32_bf16 v[24:27], v[192:195], v[184:187], v[24:27]
	v_mfma_f32_16x16x32_bf16 v[16:19], v[196:199], v[184:187], v[16:19]
	v_mfma_f32_16x16x32_bf16 v[28:31], v[200:203], v[184:187], v[28:31]
	v_mfma_f32_16x16x32_bf16 v[20:23], v[204:207], v[184:187], v[20:23]
	v_mfma_f32_16x16x32_bf16 v[56:59], v[224:227], v[208:211], v[56:59]
	v_mfma_f32_16x16x32_bf16 v[48:51], v[228:231], v[208:211], v[48:51]
	v_mfma_f32_16x16x32_bf16 v[60:63], v[232:235], v[208:211], v[60:63]
	v_mfma_f32_16x16x32_bf16 v[52:55], v[236:239], v[208:211], v[52:55]
	v_mfma_f32_16x16x32_bf16 v[40:43], v[224:227], v[212:215], v[40:43]
	v_mfma_f32_16x16x32_bf16 v[32:35], v[228:231], v[212:215], v[32:35]
	v_mfma_f32_16x16x32_bf16 v[44:47], v[232:235], v[212:215], v[44:47]
	v_mfma_f32_16x16x32_bf16 v[36:39], v[236:239], v[212:215], v[36:39]
	v_mfma_f32_16x16x32_bf16 v[24:27], v[224:227], v[216:219], v[24:27]
	v_mfma_f32_16x16x32_bf16 v[16:19], v[228:231], v[216:219], v[16:19]
	v_mfma_f32_16x16x32_bf16 v[28:31], v[232:235], v[216:219], v[28:31]
	v_mfma_f32_16x16x32_bf16 v[20:23], v[236:239], v[216:219], v[20:23]
	s_branch .Le1_skipc
.Le1_v2:
	s_lshl_b32 s28, s27, 15
	s_add_i32 s28, s28, 0
	v_lshlrev_b32_e32 v176, 1, v163
	v_add_u32_e32 v192, s28, v176
	v_lshlrev_b32_e32 v208, 1, v164
	v_lshl_add_u32 v224, v165, 1, s28
	v_add_u32_e32 v177, v192, v208
	v_add3_u32 v188, s28, v208, v176
	v_add_u32_e32 v204, v192, v175
	v_add_u32_e32 v220, v224, v208
	v_add_u32_e32 v236, v224, v175
	ds_read_b128 v[176:179], v177
	ds_read_b128 v[180:183], v188 offset:2048
	ds_read_b128 v[192:195], v204 offset:16384
	ds_read_b128 v[196:199], v204 offset:18432
	ds_read_b128 v[200:203], v204 offset:20480
	ds_read_b128 v[204:207], v204 offset:22528
	ds_read_b128 v[208:211], v220
	ds_read_b128 v[212:215], v220 offset:2048
	ds_read_b128 v[224:227], v236 offset:16384
	ds_read_b128 v[228:231], v236 offset:18432
	ds_read_b128 v[232:235], v236 offset:20480
	ds_read_b128 v[236:239], v236 offset:22528
	s_waitcnt lgkmcnt(0)
	v_mfma_f32_16x16x32_bf16 v[56:59], v[192:195], v[176:179], v[56:59]
	v_mfma_f32_16x16x32_bf16 v[48:51], v[196:199], v[176:179], v[48:51]
	v_mfma_f32_16x16x32_bf16 v[60:63], v[200:203], v[176:179], v[60:63]
	v_mfma_f32_16x16x32_bf16 v[52:55], v[204:207], v[176:179], v[52:55]
	v_mfma_f32_16x16x32_bf16 v[40:43], v[192:195], v[180:183], v[40:43]
	v_mfma_f32_16x16x32_bf16 v[32:35], v[196:199], v[180:183], v[32:35]
	v_mfma_f32_16x16x32_bf16 v[44:47], v[200:203], v[180:183], v[44:47]
	v_mfma_f32_16x16x32_bf16 v[36:39], v[204:207], v[180:183], v[36:39]
	v_mfma_f32_16x16x32_bf16 v[56:59], v[224:227], v[208:211], v[56:59]
	v_mfma_f32_16x16x32_bf16 v[48:51], v[228:231], v[208:211], v[48:51]
	v_mfma_f32_16x16x32_bf16 v[60:63], v[232:235], v[208:211], v[60:63]
	v_mfma_f32_16x16x32_bf16 v[52:55], v[236:239], v[208:211], v[52:55]
	v_mfma_f32_16x16x32_bf16 v[40:43], v[224:227], v[212:215], v[40:43]
	v_mfma_f32_16x16x32_bf16 v[32:35], v[228:231], v[212:215], v[32:35]
	v_mfma_f32_16x16x32_bf16 v[44:47], v[232:235], v[212:215], v[44:47]
	v_mfma_f32_16x16x32_bf16 v[36:39], v[236:239], v[212:215], v[36:39]
	s_branch .Le1_skipc
.Le1_v1:
	s_lshl_b32 s28, s27, 15
	s_add_i32 s28, s28, 0
	v_lshlrev_b32_e32 v176, 1, v163
	v_add_u32_e32 v192, s28, v176
	v_lshlrev_b32_e32 v208, 1, v164
	v_lshl_add_u32 v224, v165, 1, s28
	v_add_u32_e32 v177, v192, v208
	v_add3_u32 v188, s28, v208, v176
	v_add_u32_e32 v204, v192, v175
	v_add_u32_e32 v220, v224, v208
	v_add_u32_e32 v236, v224, v175
	ds_read_b128 v[176:179], v177
	ds_read_b128 v[192:195], v204 offset:16384
	ds_read_b128 v[196:199], v204 offset:18432
	ds_read_b128 v[200:203], v204 offset:20480
	ds_read_b128 v[204:207], v204 offset:22528
	ds_read_b128 v[208:211], v220
	ds_read_b128 v[224:227], v236 offset:16384
	ds_read_b128 v[228:231], v236 offset:18432
	ds_read_b128 v[232:235], v236 offset:20480
	ds_read_b128 v[236:239], v236 offset:22528
	s_waitcnt lgkmcnt(0)
	v_mfma_f32_16x16x32_bf16 v[56:59], v[192:195], v[176:179], v[56:59]
	v_mfma_f32_16x16x32_bf16 v[48:51], v[196:199], v[176:179], v[48:51]
	v_mfma_f32_16x16x32_bf16 v[60:63], v[200:203], v[176:179], v[60:63]
	v_mfma_f32_16x16x32_bf16 v[52:55], v[204:207], v[176:179], v[52:55]
	v_mfma_f32_16x16x32_bf16 v[56:59], v[224:227], v[208:211], v[56:59]
	v_mfma_f32_16x16x32_bf16 v[48:51], v[228:231], v[208:211], v[48:51]
	v_mfma_f32_16x16x32_bf16 v[60:63], v[232:235], v[208:211], v[60:63]
	v_mfma_f32_16x16x32_bf16 v[52:55], v[236:239], v[208:211], v[52:55]
	s_branch .Le1_skipc

; template <class F>
; __device__ __forceinline__ void xcd_queue_run(unsigned* qwords, int nper, char* smem_aux, F fn) {
;     ...
;       if (threadIdx.x == 0) *slot = (int)__hip_atomic_fetch_add(qwords + 64 * j, 1u, __ATOMIC_RELAXED, __HIP_MEMORY_SCOPE_AGENT);
;       __syncthreads();
;       const int q = *slot;
;       if (q >= nper) break;
; __device__ void phaseE2(const Params& p, char* smem) {
;     ...
;   xcd_queue_run(p.bar + QW_BASE + 1536, s_rb[NEXP], smem + 2 * GEMM_SMEM + 800, [&](int j, int q) {
;     const int rbg = q, nt = j;
;     int e = 0;
;     while (s_rb[e + 1] <= rbg) e++;
;     const int rb = rbg - s_rb[e];
;     const int cnt = p.cnt[e];
;     const int rows = min(128, cnt - rb * 128);
;     const int slot0 = s_off[e] + rb * 128;
;     const int n0 = nt * 128;
;     const float* wd = p.w_down + (size_t)e * DEXP * DM;
;     const float* lg = p.list_gate + e * CAP + rb * 128;
;     auto rowf = [&](int r) { int rr = r < rows ? r : 0; return (const void*)(p.H + (size_t)(slot0 + rr) * DEXP); };
.Le2_nopoll:
.LBB0_1355:
	s_or_b64 exec, exec, s[16:17]
	s_cmp_lg_u32 s33, -1
	s_cselect_b32 s2, s33, 0
	s_cselect_b32 s16, s1, 0
	v_mov_b32_e32 v0, s2
	v_mov_b32_e32 v1, s16
	s_waitcnt lgkmcnt(0)
	s_barrier
	flat_load_dword v2, v[0:1] sc0 sc1
	s_waitcnt vmcnt(0)
	s_mov_b64 s[18:19], -1
	s_waitcnt lgkmcnt(0)
	v_cmp_lt_i32_e32 vcc, v2, v108
	s_and_saveexec_b64 s[16:17], vcc
	s_cbranch_execz .LBB0_1350
	s_mov_b64 s[18:19], 0
	v_mbcnt_lo_u32_b32 v3, -1, 0
	v_mbcnt_hi_u32_b32 v3, -1, v3
	v_lshl_add_u32 v3, v3, 2, s24
	ds_read_b32 v3, v3
	s_waitcnt lgkmcnt(0)
	v_cmp_le_i32_e32 vcc, v3, v2
	s_bcnt1_i32_b64 s2, vcc
	v_mov_b32_e32 v80, s2
	s_lshl_b32 s20, s2, 21
	s_mov_b32 s21, 0
	v_lshl_add_u64 v[96:97], v[90:91], 0, s[20:21]
	s_or_b64 exec, exec, s[18:19]
	v_mul_u32_u24_e32 v0, 0x20100, v80
	v_mov_b32_e32 v1, 0
	v_lshl_add_u64 v[0:1], v[0:1], 0, s[62:63]
	global_load_dword v3, v[0:1], off
	v_lshl_add_u32 v4, v80, 2, 0
	v_lshlrev_b64 v[0:1], 21, v[80:81]
	v_add_u32_e32 v5, 0x10120, v4
	v_add_u32_e32 v4, 0x10000, v4
	v_lshl_add_u64 v[0:1], v[92:93], 0, v[0:1]
	ds_read_b32 v22, v5
	ds_read_b32 v23, v4
	v_add_co_u32_e32 v4, vcc, s26, v0
	v_mov_b32_e32 v64, 0
	s_nop 0
	v_addc_co_u32_e32 v5, vcc, 0, v1, vcc
	v_add_co_u32_e32 v6, vcc, s27, v0
	s_waitcnt lgkmcnt(1)
	v_sub_u32_e32 v2, v2, v22
	v_addc_co_u32_e32 v7, vcc, 0, v1, vcc
	v_add_co_u32_e32 v8, vcc, s28, v0
	v_lshlrev_b32_e32 v98, 7, v2
	s_nop 0
	v_addc_co_u32_e32 v9, vcc, 0, v1, vcc
	v_add_co_u32_e32 v10, vcc, s29, v0
	s_waitcnt lgkmcnt(0)
	v_add_u32_e32 v117, v23, v98
	v_addc_co_u32_e32 v11, vcc, 0, v1, vcc
	v_add_co_u32_e32 v12, vcc, s30, v0
	s_mov_b32 s2, 0
	s_nop 0
	v_addc_co_u32_e32 v13, vcc, 0, v1, vcc
	v_add_co_u32_e32 v14, vcc, s31, v0
	s_mov_b32 s47, 0
	s_nop 0
	v_addc_co_u32_e32 v15, vcc, 0, v1, vcc
	v_add_co_u32_e32 v16, vcc, s36, v0
	v_mov_b32_e32 v65, v64
	s_nop 0
	v_addc_co_u32_e32 v17, vcc, 0, v1, vcc
	v_add_co_u32_e32 v18, vcc, s25, v0
	global_load_dword v141, v[0:1], off
	global_load_dword v99, v[4:5], off offset:-4096
	global_load_dword v119, v[4:5], off
	global_load_dword v120, v[6:7], off offset:-4096
	global_load_dword v121, v[6:7], off
	global_load_dword v122, v[8:9], off offset:-4096
	global_load_dword v123, v[8:9], off
	global_load_dword v128, v[10:11], off offset:-4096
	global_load_dword v130, v[10:11], off
	global_load_dword v132, v[12:13], off offset:-4096
	global_load_dword v133, v[12:13], off
	global_load_dword v134, v[14:15], off offset:-4096
	global_load_dword v135, v[14:15], off
	global_load_dword v136, v[16:17], off offset:-4096
	global_load_dword v137, v[16:17], off
	v_addc_co_u32_e32 v19, vcc, 0, v1, vcc
	v_add_co_u32_e32 v20, vcc, s37, v0
	v_mov_b32_e32 v66, v64
	s_nop 0
	v_addc_co_u32_e32 v21, vcc, 0, v1, vcc
	v_mov_b32_e32 v67, v64
	v_mov_b32_e32 v76, v64
	v_mov_b32_e32 v77, v64
	v_mov_b32_e32 v78, v64
	v_mov_b32_e32 v79, v64
	v_mov_b32_e32 v72, v64
	v_mov_b32_e32 v73, v64
	v_mov_b32_e32 v74, v64
	v_mov_b32_e32 v75, v64
	v_mov_b32_e32 v68, v64
	v_mov_b32_e32 v69, v64
	v_mov_b32_e32 v70, v64
	v_mov_b32_e32 v71, v64
	v_mov_b32_e32 v60, v64
	v_mov_b32_e32 v61, v64
	v_mov_b32_e32 v62, v64
	v_mov_b32_e32 v63, v64
	v_mov_b32_e32 v56, v64
	v_mov_b32_e32 v57, v64
	v_mov_b32_e32 v58, v64
	v_mov_b32_e32 v59, v64
	v_mov_b32_e32 v52, v64
	v_mov_b32_e32 v53, v64
	v_mov_b32_e32 v54, v64
	v_mov_b32_e32 v55, v64
	v_mov_b32_e32 v48, v64
	v_mov_b32_e32 v49, v64
	v_mov_b32_e32 v50, v64
	s_waitcnt vmcnt(15)
; template <bool ABF, bool BBF, class RowF, class ColF, class Epi>
; __device__ __forceinline__ void gemm_tile(char* smem, int K, RowF rowptr, ColF colptr, int ldb, Epi epi) {
;     ...
;   auto gload = [&](int k0) {
; #pragma unroll
;     for (int i = 0; i < NA; i++) ra[i] = *(const u32x4*)(ap[i] + (size_t)k0 * (ABF ? 2 : 4));
;     if (BBF) {
; #pragma unroll
;       for (int i = 0; i < 4; i++) rbb[BBF ? i : 0] = *(const u32x4*)(bq[i] + (size_t)k0 * 2);
;     } else {
;       const float* b = bp + (size_t)k0 * ldb;
; #pragma unroll
;       for (int j = 0; j < 32; j++) rb[BBF ? 0 : j] = b[(size_t)j * ldb];
;     }
;   };
;   auto sstore = [&](int buf) {
;     u16* As = As0 + buf * (GEMM_SMEM / 2);
;     u16* Bs = As + BM * LDT;
; #pragma unroll
;     for (int i = 0; i < NA; i++) {
;       if (ABF) {
;         { const int row = ar0 + ARS * i; *(u32x4*)&As[row * LDT + (((ac >> 3) ^ ((row >> 1) & 7)) << 3)] = ra[i]; }
;       } else {
;         u32x2 v;
;         v[0] = pack2(__uint_as_float(ra[i][0]), __uint_as_float(ra[i][1]));
;         v[1] = pack2(__uint_as_float(ra[i][2]), __uint_as_float(ra[i][3]));
;         { const int row = ar0 + ARS * i; *(u32x2*)&As[row * LDT + (((ac >> 3) ^ ((row >> 1) & 7)) << 3) + (ac & 4)] = v; }
;       }
;     }
;     if (BBF) {
; #pragma unroll
;       for (int i = 0; i < 4; i++) { const int row = br0 + 32 * i; *(u32x4*)&Bs[row * LDT + (((bcc >> 3) ^ ((row >> 1) & 7)) << 3)] = rbb[BBF ? i : 0]; }
;     } else {
; #pragma unroll
;       for (int j = 0; j < 4; j++) {
;         u32x4 v;
;         v[0] = pack2(rb[BBF ? 0 : 8 * j + 0], rb[BBF ? 0 : 8 * j + 1]);
;         v[1] = pack2(rb[BBF ? 0 : 8 * j + 2], rb[BBF ? 0 : 8 * j + 3]);
;         v[2] = pack2(rb[BBF ? 0 : 8 * j + 4], rb[BBF ? 0 : 8 * j + 5]);
;         v[3] = pack2(rb[BBF ? 0 : 8 * j + 6], rb[BBF ? 0 : 8 * j + 7]);
;         *(u32x4*)&Bs[bc * LDT + (((kh * 4 + j) ^ ((bc >> 1) & 7)) << 3)] = v;
;       }
;     }
;   };
;   gload(0);
; __device__ void phaseE2(const Params& p, char* smem) {
;     ...
;     const int cnt = p.cnt[e];
;     const int rows = min(128, cnt - rb * 128);
;     const int slot0 = s_off[e] + rb * 128;
;     const int n0 = nt * 128;
;     const float* wd = p.w_down + (size_t)e * DEXP * DM;
;     const float* lg = p.list_gate + e * CAP + rb * 128;
;     auto rowf = [&](int r) { int rr = r < rows ? r : 0; return (const void*)(p.H + (size_t)(slot0 + rr) * DEXP); };
	v_sub_u32_e32 v2, v3, v98
	v_min_i32_e32 v118, 0x80, v2
	v_cmp_lt_i32_e32 vcc, v160, v118
	v_mov_b32_e32 v51, v64
	v_mov_b32_e32 v28, v64
	v_cndmask_b32_e32 v2, 0, v160, vcc
	v_cmp_lt_i32_e32 vcc, v150, v118
	v_add_u32_e32 v2, v2, v117
	v_mov_b32_e32 v29, v64
	v_cndmask_b32_e32 v3, 0, v150, vcc
	v_cmp_lt_i32_e32 vcc, v151, v118
	v_add_u32_e32 v4, v3, v117
	v_ashrrev_i32_e32 v3, 31, v2
	v_cndmask_b32_e32 v5, 0, v151, vcc
	v_cmp_lt_i32_e32 vcc, v152, v118
	v_add_u32_e32 v6, v5, v117
	v_ashrrev_i32_e32 v5, 31, v4
	v_cndmask_b32_e32 v7, 0, v152, vcc
	v_add_co_u32_e32 v10, vcc, s38, v0
	v_add_u32_e32 v8, v7, v117
	s_nop 0
	v_addc_co_u32_e32 v11, vcc, 0, v1, vcc
	v_add_co_u32_e32 v12, vcc, s39, v0
	v_ashrrev_i32_e32 v7, 31, v6
	s_nop 0
	v_addc_co_u32_e32 v13, vcc, 0, v1, vcc
	global_load_dword v138, v[18:19], off offset:-4096
	global_load_dword v139, v[18:19], off
	global_load_dword v140, v[20:21], off offset:-4096
	global_load_dword v142, v[20:21], off
	global_load_dword v143, v[10:11], off offset:-4096
	global_load_dword v144, v[10:11], off
	global_load_dword v145, v[12:13], off offset:-4096
	global_load_dword v146, v[12:13], off
	v_add_co_u32_e32 v10, vcc, s40, v0
	v_lshlrev_b64 v[16:17], 10, v[2:3]
	s_nop 0
	v_addc_co_u32_e32 v11, vcc, 0, v1, vcc
	v_add_co_u32_e32 v12, vcc, s41, v0
	v_ashrrev_i32_e32 v9, 31, v8
	s_nop 0
	v_addc_co_u32_e32 v13, vcc, 0, v1, vcc
	v_add_co_u32_e32 v14, vcc, s42, v0
	v_lshlrev_b64 v[22:23], 10, v[4:5]
	s_nop 0
	v_addc_co_u32_e32 v15, vcc, 0, v1, vcc
	v_add_co_u32_e32 v18, vcc, s43, v0
	v_lshlrev_b64 v[24:25], 10, v[6:7]
	s_nop 0
	v_addc_co_u32_e32 v19, vcc, 0, v1, vcc
	v_add_co_u32_e32 v0, vcc, s44, v0
	v_lshl_add_u64 v[2:3], v[86:87], 0, v[16:17]
	s_nop 0
	v_addc_co_u32_e32 v1, vcc, 0, v1, vcc
	global_load_dword v147, v[10:11], off offset:-4096
	global_load_dword v153, v[10:11], off
	global_load_dword v154, v[12:13], off offset:-4096
	global_load_dword v155, v[12:13], off
	global_load_dword v156, v[14:15], off offset:-4096
	global_load_dword v157, v[14:15], off
	global_load_dword v158, v[18:19], off offset:-4096
	global_load_dword v159, v[18:19], off
	global_load_dword v170, v[0:1], off
	v_lshlrev_b64 v[18:19], 10, v[8:9]
	v_lshl_add_u64 v[4:5], v[86:87], 0, v[22:23]
	v_lshl_add_u64 v[6:7], v[86:87], 0, v[24:25]
	v_lshl_add_u64 v[0:1], v[86:87], 0, v[18:19]
	v_lshrrev_b32_e32 v46, 2, v149
	v_lshrrev_b32_e32 v35, 4, v46
	v_xor_b32_e32 v35, v35, v46
	v_and_b32_e32 v35, 7, v35
	v_lshlrev_b32_e32 v34, 4, v35
	v_mov_b32_e32 v35, 0
	v_sub_u32_e32 v38, v34, v124
	v_lshrrev_b32_e32 v46, 6, v46
	v_ashrrev_i32_e32 v39, 31, v38
	v_readfirstlane_b32 s100, v46
	s_lshl_b32 s100, s100, 10
	v_readfirstlane_b32 s98, v118
	s_lshr_b32 s99, s100, 11
	s_lshl_b32 s99, s99, 6
	s_sub_i32 s99, s98, s99
	s_max_i32 s99, s99, 0
	s_min_i32 s99, s99, 64
	s_add_i32 s99, s99, 15
	s_lshr_b32 s99, s99, 4
	s_add_u32 m0, s100, 0x0
	v_lshl_add_u64 v[42:43], v[2:3], 0, v[38:39]
	global_load_lds_dwordx4 v[42:43], off
	s_add_u32 m0, s100, 0x1000
	v_lshl_add_u64 v[42:43], v[4:5], 0, v[38:39]
	global_load_lds_dwordx4 v[42:43], off
	s_add_u32 m0, s100, 0x2000
	v_lshl_add_u64 v[42:43], v[6:7], 0, v[38:39]
	global_load_lds_dwordx4 v[42:43], off
	s_add_u32 m0, s100, 0x3000
	v_lshl_add_u64 v[42:43], v[0:1], 0, v[38:39]
	global_load_lds_dwordx4 v[42:43], off
	s_waitcnt vmcnt(34)
	v_cvt_pk_bf16_f32 v0, v141, v99
	s_waitcnt vmcnt(32)
	v_cvt_pk_bf16_f32 v1, v119, v120
	s_waitcnt vmcnt(30)
	v_cvt_pk_bf16_f32 v2, v121, v122
	s_waitcnt vmcnt(28)
	v_cvt_pk_bf16_f32 v3, v123, v128
	s_waitcnt vmcnt(26)
	v_cvt_pk_bf16_f32 v4, v130, v132
	s_waitcnt vmcnt(24)
	v_cvt_pk_bf16_f32 v5, v133, v134
	s_waitcnt vmcnt(22)
	v_cvt_pk_bf16_f32 v6, v135, v136
	v_lshl_add_u64 v[100:101], s[8:9], 0, v[16:17]
	v_lshl_add_u64 v[102:103], s[8:9], 0, v[22:23]
	v_lshl_add_u64 v[104:105], s[8:9], 0, v[24:25]
	v_lshl_add_u64 v[106:107], s[8:9], 0, v[18:19]
	v_mov_b32_e32 v30, v64
	v_mov_b32_e32 v31, v64
	v_mov_b32_e32 v24, v64
	v_mov_b32_e32 v25, v64
	v_mov_b32_e32 v26, v64
	v_mov_b32_e32 v27, v64
	v_mov_b32_e32 v20, v64
	v_mov_b32_e32 v21, v64
	v_mov_b32_e32 v22, v64
	v_mov_b32_e32 v23, v64
	v_mov_b32_e32 v16, v64
	v_mov_b32_e32 v17, v64
	v_mov_b32_e32 v18, v64
	v_mov_b32_e32 v19, v64
	s_waitcnt vmcnt(20)
	v_cvt_pk_bf16_f32 v7, v137, v138
	s_waitcnt vmcnt(18)
	v_cvt_pk_bf16_f32 v8, v139, v140
	s_waitcnt vmcnt(16)
	v_cvt_pk_bf16_f32 v9, v142, v143
	s_waitcnt vmcnt(14)
	v_cvt_pk_bf16_f32 v10, v144, v145
	s_waitcnt vmcnt(12)
	v_cvt_pk_bf16_f32 v11, v146, v147
	s_waitcnt vmcnt(10)
	v_cvt_pk_bf16_f32 v12, v153, v154
	s_waitcnt vmcnt(8)
	v_cvt_pk_bf16_f32 v13, v155, v156
	s_waitcnt vmcnt(6)
	v_cvt_pk_bf16_f32 v14, v157, v158
	s_waitcnt vmcnt(4)
	v_cvt_pk_bf16_f32 v15, v159, v170
	s_waitcnt vmcnt(3)
	s_waitcnt vmcnt(2)
	s_waitcnt vmcnt(1)
	s_waitcnt vmcnt(0)
	ds_write_b128 v113, v[0:3] offset:16384
	ds_write_b128 v114, v[4:7] offset:16384
	ds_write_b128 v115, v[8:11] offset:16384
	ds_write_b128 v116, v[12:15] offset:16384
	v_mov_b32_e32 v12, v64
	v_mov_b32_e32 v13, v64
	v_mov_b32_e32 v14, v64
	v_mov_b32_e32 v15, v64
	v_mov_b32_e32 v8, v64
	v_mov_b32_e32 v9, v64
	v_mov_b32_e32 v10, v64
	v_mov_b32_e32 v11, v64
	v_mov_b32_e32 v4, v64
	v_mov_b32_e32 v5, v64
	v_mov_b32_e32 v6, v64
	v_mov_b32_e32 v7, v64
	v_mov_b32_e32 v0, v64
	v_mov_b32_e32 v1, v64
	v_mov_b32_e32 v2, v64
	v_mov_b32_e32 v3, v64
	s_waitcnt lgkmcnt(0)
	s_barrier
	s_branch .LBB0_1360

; template <bool ABF, bool BBF, class RowF, class ColF, class Epi>
; __device__ __forceinline__ void gemm_tile(char* smem, int K, RowF rowptr, ColF colptr, int ldb, Epi epi) {
;     ...
;     {
;       bf16x8 af[2][4], bfr[2][4];
; #pragma unroll
;       for (int ks = 0; ks < 2; ks++) {
; #pragma unroll
;         for (int mi = 0; mi < 4; mi++) af[ks][mi] = *(const bf16x8*)&As[(wm * 64 + mi * 16 + l15) * LDT + (((ks * 4 + kg) ^ swz) << 3)];
; #pragma unroll
;         for (int ni = 0; ni < 4; ni++) bfr[ks][ni] = *(const bf16x8*)&Bs[(wn * 64 + ni * 16 + l15) * LDT + (((ks * 4 + kg) ^ swz) << 3)];
;       }
;       __builtin_amdgcn_sched_barrier(0);
; #pragma unroll
;       for (int ks = 0; ks < 2; ks++)
; #pragma unroll
;         for (int mi = 0; mi < 4; mi++)
; #pragma unroll
;           for (int ni = 0; ni < 4; ni++)
;             acc[mi][ni] = __builtin_amdgcn_mfma_f32_16x16x32_bf16(bfr[ks][ni], af[ks][mi], acc[mi][ni], 0, 0, 0);
;       __builtin_amdgcn_sched_barrier(0);
;     }
.LBB0_1362:
	s_cmp_lg_u32 s99, 4
	s_cbranch_scc1 .Le2_var
	s_lshl_b32 s48, s47, 15
	s_add_i32 s48, s48, 0
	v_lshlrev_b32_e32 v220, 1, v162
	v_lshlrev_b32_e32 v171, 1, v163
	v_lshlrev_b32_e32 v204, 1, v164
	v_add_u32_e32 v221, s48, v220
	v_add3_u32 v172, s48, v171, v204
	v_add3_u32 v184, s48, v204, v171
	v_add_u32_e32 v171, v221, v171
	ds_read_b128 v[172:175], v172
	ds_read_b128 v[176:179], v184 offset:2048
	ds_read_b128 v[180:183], v184 offset:4096
	ds_read_b128 v[184:187], v184 offset:6144
	ds_read_b128 v[188:191], v171 offset:16384
	ds_read_b128 v[192:195], v171 offset:18432
	ds_read_b128 v[196:199], v171 offset:20480
	ds_read_b128 v[200:203], v171 offset:22528
	v_lshlrev_b32_e32 v171, 1, v165
	v_add_u32_e32 v222, s48, v171
	v_add_u32_e32 v216, v222, v204
	v_add_u32_e32 v220, v222, v220
	ds_read_b128 v[204:207], v216
	ds_read_b128 v[208:211], v216 offset:2048
	ds_read_b128 v[212:215], v216 offset:4096
	ds_read_b128 v[216:219], v216 offset:6144
	v_add_u32_e32 v171, v221, v171
	ds_read_b128 v[220:223], v220 offset:16384
	ds_read_b128 v[224:227], v171 offset:18432
	ds_read_b128 v[228:231], v171 offset:20480
	ds_read_b128 v[232:235], v171 offset:22528
	s_waitcnt lgkmcnt(11)
	v_mfma_f32_16x16x32_bf16 v[64:67], v[188:191], v[172:175], v[64:67]
	s_waitcnt lgkmcnt(10)
	v_mfma_f32_16x16x32_bf16 v[76:79], v[192:195], v[172:175], v[76:79]
	s_waitcnt lgkmcnt(9)
	v_mfma_f32_16x16x32_bf16 v[72:75], v[196:199], v[172:175], v[72:75]
	s_waitcnt lgkmcnt(8)
	v_mfma_f32_16x16x32_bf16 v[68:71], v[200:203], v[172:175], v[68:71]
	v_mfma_f32_16x16x32_bf16 v[60:63], v[188:191], v[176:179], v[60:63]
	v_mfma_f32_16x16x32_bf16 v[56:59], v[192:195], v[176:179], v[56:59]
	v_mfma_f32_16x16x32_bf16 v[52:55], v[196:199], v[176:179], v[52:55]
	v_mfma_f32_16x16x32_bf16 v[48:51], v[200:203], v[176:179], v[48:51]
	v_mfma_f32_16x16x32_bf16 v[28:31], v[188:191], v[180:183], v[28:31]
	v_mfma_f32_16x16x32_bf16 v[24:27], v[192:195], v[180:183], v[24:27]
	v_mfma_f32_16x16x32_bf16 v[20:23], v[196:199], v[180:183], v[20:23]
	v_mfma_f32_16x16x32_bf16 v[16:19], v[200:203], v[180:183], v[16:19]
	v_mfma_f32_16x16x32_bf16 v[12:15], v[188:191], v[184:187], v[12:15]
	v_mfma_f32_16x16x32_bf16 v[8:11], v[192:195], v[184:187], v[8:11]
	v_mfma_f32_16x16x32_bf16 v[4:7], v[196:199], v[184:187], v[4:7]
	v_mfma_f32_16x16x32_bf16 v[0:3], v[200:203], v[184:187], v[0:3]
	s_waitcnt lgkmcnt(3)
	v_mfma_f32_16x16x32_bf16 v[64:67], v[220:223], v[204:207], v[64:67]
	s_waitcnt lgkmcnt(2)
	v_mfma_f32_16x16x32_bf16 v[76:79], v[224:227], v[204:207], v[76:79]
	s_waitcnt lgkmcnt(1)
	v_mfma_f32_16x16x32_bf16 v[72:75], v[228:231], v[204:207], v[72:75]
	s_waitcnt lgkmcnt(0)
	v_mfma_f32_16x16x32_bf16 v[68:71], v[232:235], v[204:207], v[68:71]
	v_mfma_f32_16x16x32_bf16 v[60:63], v[220:223], v[208:211], v[60:63]
	v_mfma_f32_16x16x32_bf16 v[56:59], v[224:227], v[208:211], v[56:59]
	v_mfma_f32_16x16x32_bf16 v[52:55], v[228:231], v[208:211], v[52:55]
	v_mfma_f32_16x16x32_bf16 v[48:51], v[232:235], v[208:211], v[48:51]
	v_mfma_f32_16x16x32_bf16 v[28:31], v[220:223], v[212:215], v[28:31]
	v_mfma_f32_16x16x32_bf16 v[24:27], v[224:227], v[212:215], v[24:27]
	v_mfma_f32_16x16x32_bf16 v[20:23], v[228:231], v[212:215], v[20:23]
	v_mfma_f32_16x16x32_bf16 v[16:19], v[232:235], v[212:215], v[16:19]
	v_mfma_f32_16x16x32_bf16 v[12:15], v[220:223], v[216:219], v[12:15]
	v_mfma_f32_16x16x32_bf16 v[8:11], v[224:227], v[216:219], v[8:11]
	v_mfma_f32_16x16x32_bf16 v[4:7], v[228:231], v[216:219], v[4:7]
	v_mfma_f32_16x16x32_bf16 v[0:3], v[232:235], v[216:219], v[0:3]

; template <bool ABF, bool BBF, class RowF, class ColF, class Epi>
; __device__ __forceinline__ void gemm_tile(char* smem, int K, RowF rowptr, ColF colptr, int ldb, Epi epi) {
;     ...
;     {
;       bf16x8 af[2][4], bfr[2][4];
; #pragma unroll
;       for (int ks = 0; ks < 2; ks++) {
; #pragma unroll
;         for (int mi = 0; mi < 4; mi++) af[ks][mi] = *(const bf16x8*)&As[(wm * 64 + mi * 16 + l15) * LDT + (((ks * 4 + kg) ^ swz) << 3)];
; #pragma unroll
;         for (int ni = 0; ni < 4; ni++) bfr[ks][ni] = *(const bf16x8*)&Bs[(wn * 64 + ni * 16 + l15) * LDT + (((ks * 4 + kg) ^ swz) << 3)];
;       }
;       __builtin_amdgcn_sched_barrier(0);
; #pragma unroll
;       for (int ks = 0; ks < 2; ks++)
; #pragma unroll
;         for (int mi = 0; mi < 4; mi++)
; #pragma unroll
;           for (int ni = 0; ni < 4; ni++)
;             acc[mi][ni] = __builtin_amdgcn_mfma_f32_16x16x32_bf16(bfr[ks][ni], af[ks][mi], acc[mi][ni], 0, 0, 0);
;       __builtin_amdgcn_sched_barrier(0);
;     }
.Le2_var:
	s_cmp_eq_u32 s99, 0
	s_cbranch_scc1 .Le2_skipc
	s_cmp_eq_u32 s99, 1
	s_cbranch_scc1 .Le2_v1
	s_cmp_eq_u32 s99, 2
	s_cbranch_scc1 .Le2_v2
	s_lshl_b32 s48, s47, 15
	s_add_i32 s48, s48, 0
	v_lshlrev_b32_e32 v220, 1, v162
	v_lshlrev_b32_e32 v171, 1, v163
	v_lshlrev_b32_e32 v204, 1, v164
	v_add_u32_e32 v221, s48, v220
	v_add3_u32 v172, s48, v171, v204
	v_add3_u32 v184, s48, v204, v171
	v_add_u32_e32 v171, v221, v171
	ds_read_b128 v[172:175], v172
	ds_read_b128 v[176:179], v184 offset:2048
	ds_read_b128 v[180:183], v184 offset:4096
	ds_read_b128 v[188:191], v171 offset:16384
	ds_read_b128 v[192:195], v171 offset:18432
	ds_read_b128 v[196:199], v171 offset:20480
	ds_read_b128 v[200:203], v171 offset:22528
	v_lshlrev_b32_e32 v171, 1, v165
	v_add_u32_e32 v222, s48, v171
	v_add_u32_e32 v216, v222, v204
	v_add_u32_e32 v220, v222, v220
	ds_read_b128 v[204:207], v216
	ds_read_b128 v[208:211], v216 offset:2048
	ds_read_b128 v[212:215], v216 offset:4096
	v_add_u32_e32 v171, v221, v171
	ds_read_b128 v[220:223], v220 offset:16384
	ds_read_b128 v[224:227], v171 offset:18432
	ds_read_b128 v[228:231], v171 offset:20480
	ds_read_b128 v[232:235], v171 offset:22528
	s_waitcnt lgkmcnt(0)
	v_mfma_f32_16x16x32_bf16 v[64:67], v[188:191], v[172:175], v[64:67]
	v_mfma_f32_16x16x32_bf16 v[76:79], v[192:195], v[172:175], v[76:79]
	v_mfma_f32_16x16x32_bf16 v[72:75], v[196:199], v[172:175], v[72:75]
	v_mfma_f32_16x16x32_bf16 v[68:71], v[200:203], v[172:175], v[68:71]
	v_mfma_f32_16x16x32_bf16 v[60:63], v[188:191], v[176:179], v[60:63]
	v_mfma_f32_16x16x32_bf16 v[56:59], v[192:195], v[176:179], v[56:59]
	v_mfma_f32_16x16x32_bf16 v[52:55], v[196:199], v[176:179], v[52:55]
	v_mfma_f32_16x16x32_bf16 v[48:51], v[200:203], v[176:179], v[48:51]
	v_mfma_f32_16x16x32_bf16 v[28:31], v[188:191], v[180:183], v[28:31]
	v_mfma_f32_16x16x32_bf16 v[24:27], v[192:195], v[180:183], v[24:27]
	v_mfma_f32_16x16x32_bf16 v[20:23], v[196:199], v[180:183], v[20:23]
	v_mfma_f32_16x16x32_bf16 v[16:19], v[200:203], v[180:183], v[16:19]
	v_mfma_f32_16x16x32_bf16 v[64:67], v[220:223], v[204:207], v[64:67]
	v_mfma_f32_16x16x32_bf16 v[76:79], v[224:227], v[204:207], v[76:79]
	v_mfma_f32_16x16x32_bf16 v[72:75], v[228:231], v[204:207], v[72:75]
	v_mfma_f32_16x16x32_bf16 v[68:71], v[232:235], v[204:207], v[68:71]
	v_mfma_f32_16x16x32_bf16 v[60:63], v[220:223], v[208:211], v[60:63]
	v_mfma_f32_16x16x32_bf16 v[56:59], v[224:227], v[208:211], v[56:59]
	v_mfma_f32_16x16x32_bf16 v[52:55], v[228:231], v[208:211], v[52:55]
	v_mfma_f32_16x16x32_bf16 v[48:51], v[232:235], v[208:211], v[48:51]
	v_mfma_f32_16x16x32_bf16 v[28:31], v[220:223], v[212:215], v[28:31]
	v_mfma_f32_16x16x32_bf16 v[24:27], v[224:227], v[212:215], v[24:27]
	v_mfma_f32_16x16x32_bf16 v[20:23], v[228:231], v[212:215], v[20:23]
	v_mfma_f32_16x16x32_bf16 v[16:19], v[232:235], v[212:215], v[16:19]
	s_branch .Le2_skipc
.Le2_v2:
	s_lshl_b32 s48, s47, 15
	s_add_i32 s48, s48, 0
	v_lshlrev_b32_e32 v220, 1, v162
	v_lshlrev_b32_e32 v171, 1, v163
	v_lshlrev_b32_e32 v204, 1, v164
	v_add_u32_e32 v221, s48, v220
	v_add3_u32 v172, s48, v171, v204
	v_add3_u32 v184, s48, v204, v171
	v_add_u32_e32 v171, v221, v171
	ds_read_b128 v[172:175], v172
	ds_read_b128 v[176:179], v184 offset:2048
	ds_read_b128 v[188:191], v171 offset:16384
	ds_read_b128 v[192:195], v171 offset:18432
	ds_read_b128 v[196:199], v171 offset:20480
	ds_read_b128 v[200:203], v171 offset:22528
	v_lshlrev_b32_e32 v171, 1, v165
	v_add_u32_e32 v222, s48, v171
	v_add_u32_e32 v216, v222, v204
	v_add_u32_e32 v220, v222, v220
	ds_read_b128 v[204:207], v216
	ds_read_b128 v[208:211], v216 offset:2048
	v_add_u32_e32 v171, v221, v171
	ds_read_b128 v[220:223], v220 offset:16384
	ds_read_b128 v[224:227], v171 offset:18432
	ds_read_b128 v[228:231], v171 offset:20480
	ds_read_b128 v[232:235], v171 offset:22528
	s_waitcnt lgkmcnt(0)
	v_mfma_f32_16x16x32_bf16 v[64:67], v[188:191], v[172:175], v[64:67]
	v_mfma_f32_16x16x32_bf16 v[76:79], v[192:195], v[172:175], v[76:79]
	v_mfma_f32_16x16x32_bf16 v[72:75], v[196:199], v[172:175], v[72:75]
	v_mfma_f32_16x16x32_bf16 v[68:71], v[200:203], v[172:175], v[68:71]
	v_mfma_f32_16x16x32_bf16 v[60:63], v[188:191], v[176:179], v[60:63]
	v_mfma_f32_16x16x32_bf16 v[56:59], v[192:195], v[176:179], v[56:59]
	v_mfma_f32_16x16x32_bf16 v[52:55], v[196:199], v[176:179], v[52:55]
	v_mfma_f32_16x16x32_bf16 v[48:51], v[200:203], v[176:179], v[48:51]
	v_mfma_f32_16x16x32_bf16 v[64:67], v[220:223], v[204:207], v[64:67]
	v_mfma_f32_16x16x32_bf16 v[76:79], v[224:227], v[204:207], v[76:79]
	v_mfma_f32_16x16x32_bf16 v[72:75], v[228:231], v[204:207], v[72:75]
	v_mfma_f32_16x16x32_bf16 v[68:71], v[232:235], v[204:207], v[68:71]
	v_mfma_f32_16x16x32_bf16 v[60:63], v[220:223], v[208:211], v[60:63]
	v_mfma_f32_16x16x32_bf16 v[56:59], v[224:227], v[208:211], v[56:59]
	v_mfma_f32_16x16x32_bf16 v[52:55], v[228:231], v[208:211], v[52:55]
	v_mfma_f32_16x16x32_bf16 v[48:51], v[232:235], v[208:211], v[48:51]
	s_branch .Le2_skipc
.Le2_v1:
	s_lshl_b32 s48, s47, 15
	s_add_i32 s48, s48, 0
	v_lshlrev_b32_e32 v220, 1, v162
	v_lshlrev_b32_e32 v171, 1, v163
	v_lshlrev_b32_e32 v204, 1, v164
	v_add_u32_e32 v221, s48, v220
	v_add3_u32 v172, s48, v171, v204
	v_add3_u32 v184, s48, v204, v171
	v_add_u32_e32 v171, v221, v171
	ds_read_b128 v[172:175], v172
	ds_read_b128 v[188:191], v171 offset:16384
	ds_read_b128 v[192:195], v171 offset:18432
	ds_read_b128 v[196:199], v171 offset:20480
	ds_read_b128 v[200:203], v171 offset:22528
	v_lshlrev_b32_e32 v171, 1, v165
	v_add_u32_e32 v222, s48, v171
	v_add_u32_e32 v216, v222, v204
	v_add_u32_e32 v220, v222, v220
	ds_read_b128 v[204:207], v216
	v_add_u32_e32 v171, v221, v171
	ds_read_b128 v[220:223], v220 offset:16384
	ds_read_b128 v[224:227], v171 offset:18432
	ds_read_b128 v[228:231], v171 offset:20480
	ds_read_b128 v[232:235], v171 offset:22528
	s_waitcnt lgkmcnt(0)
	v_mfma_f32_16x16x32_bf16 v[64:67], v[188:191], v[172:175], v[64:67]
	v_mfma_f32_16x16x32_bf16 v[76:79], v[192:195], v[172:175], v[76:79]
	v_mfma_f32_16x16x32_bf16 v[72:75], v[196:199], v[172:175], v[72:75]
	v_mfma_f32_16x16x32_bf16 v[68:71], v[200:203], v[172:175], v[68:71]
	v_mfma_f32_16x16x32_bf16 v[64:67], v[220:223], v[204:207], v[64:67]
	v_mfma_f32_16x16x32_bf16 v[76:79], v[224:227], v[204:207], v[76:79]
	v_mfma_f32_16x16x32_bf16 v[72:75], v[228:231], v[204:207], v[72:75]
	v_mfma_f32_16x16x32_bf16 v[68:71], v[232:235], v[204:207], v[68:71]
	s_branch .Le2_skipc
